# ssm pass 3 scan: B_bar*u dot chains of the four steps interleaved eight-way, state updates back to back
# speedup vs baseline: 1.0135x; 1.0015x over previous
; __device__ __forceinline__ void ssm_pass3h(CArgs* ap, const float* COEF, int l, const bf16_t* PROJ, const float* SST, bf16_t* YS, LAS unsigned char* wlds, int unit, int lane) {
;     ...
;             u32x4 wc[8];
; #pragma unroll
;             for (int j = 0; j < 8; ++j) wc[j] = wn[j];
;             const int tn = (t + 4 < 128) ? t + 4 : t;
; #pragma unroll
;             for (int tt = 0; tt < 4; ++tt) { wn[2 * tt] = ((const u32x4*)(up + (size_t)(tn + tt) * INW))[0]; wn[2 * tt + 1] = ((const u32x4*)(up + (size_t)(tn + tt) * INW))[1]; }
; #pragma unroll
;             for (int tt = 0; tt < 4; ++tt) {
;                 const u32x4 w0 = wc[2 * tt], w1 = wc[2 * tt + 1];
;                 const unsigned u2[8] = {w0.x, w0.y, w0.z, w0.w, w1.x, w1.y, w1.z, w1.w};
;                 float br_ = 0.f, bi_ = 0.f;
; #pragma unroll
;                 for (int k = 0; k < 8; ++k) { br_ = __builtin_amdgcn_fdot2_f32_bf16(__builtin_bit_cast(bf16x2v, bbr2[k]), __builtin_bit_cast(bf16x2v, u2[k]), br_, false);
;                                                bi_ = __builtin_amdgcn_fdot2_f32_bf16(__builtin_bit_cast(bf16x2v, bbi2[k]), __builtin_bit_cast(bf16x2v, u2[k]), bi_, false); }
;                 const float nr = abr * hr - abi * hi + br_, ni = abr * hi + abi * hr + bi_; hr = nr; hi = ni;
;                 Hf[(4 * q + tt) * 132 + lane] = hr; Hf[(4 * q + tt) * 132 + 64 + lane] = hi;
;             }
.LBB0_150:
	s_add_i32 s13, s14, 4
	s_cmpk_lt_u32 s14, 0x7c
	s_cselect_b32 s14, s13, s14
	s_mul_i32 s78, s14, 0x2400
	s_lshl_b64 s[14:15], s[78:79], 1
	s_add_u32 s14, s2, s14
	s_waitcnt vmcnt(7)
	v_mov_b64_e32 v[138:139], v[22:23]
	s_waitcnt vmcnt(6)
	v_mov_b64_e32 v[142:143], v[26:27]
	s_addc_u32 s15, s3, s15
	v_mov_b64_e32 v[136:137], v[20:21]
	v_mov_b64_e32 v[140:141], v[24:25]
	global_load_dwordx4 v[20:23], v1, s[14:15] offset:16
	global_load_dwordx4 v[24:27], v1, s[14:15]
	s_add_i32 s14, s78, 0x2400
	s_mov_b32 s15, s79
	s_lshl_b64 s[14:15], s[14:15], 1
	s_add_u32 s14, s2, s14
	s_waitcnt vmcnt(7)
	v_mov_b64_e32 v[70:71], v[30:31]
	s_waitcnt vmcnt(6)
	v_mov_b64_e32 v[74:75], v[34:35]
	s_addc_u32 s15, s3, s15
	v_mov_b64_e32 v[68:69], v[28:29]
	v_mov_b64_e32 v[72:73], v[32:33]
	global_load_dwordx4 v[28:31], v1, s[14:15] offset:16
	global_load_dwordx4 v[32:35], v1, s[14:15]
	s_add_i32 s14, s78, 0x4800
	s_mov_b32 s15, s79
	s_lshl_b64 s[14:15], s[14:15], 1
	s_add_u32 s14, s2, s14
	s_waitcnt vmcnt(7)
	v_mov_b64_e32 v[62:63], v[38:39]
	s_waitcnt vmcnt(6)
	v_mov_b64_e32 v[66:67], v[42:43]
	s_addc_u32 s15, s3, s15
	s_addk_i32 s78, 0x6c00
	v_mov_b64_e32 v[60:61], v[36:37]
	v_mov_b64_e32 v[64:65], v[40:41]
	global_load_dwordx4 v[36:39], v1, s[14:15] offset:16
	global_load_dwordx4 v[40:43], v1, s[14:15]
	s_lshl_b64 s[14:15], s[78:79], 1
	s_add_u32 s14, s2, s14
	s_waitcnt vmcnt(7)
	v_mov_b64_e32 v[54:55], v[46:47]
	s_waitcnt vmcnt(6)
	v_mov_b64_e32 v[58:59], v[50:51]
	s_addc_u32 s15, s3, s15
	v_mov_b64_e32 v[52:53], v[44:45]
	v_mov_b64_e32 v[56:57], v[48:49]
	global_load_dwordx4 v[44:47], v1, s[14:15] offset:16
	global_load_dwordx4 v[48:51], v1, s[14:15]
	v_mov_b32_e32 v144, 0
	v_mov_b32_e32 v145, 0
	v_mov_b32_e32 v146, 0
	v_mov_b32_e32 v147, 0
	v_mov_b32_e32 v148, 0
	v_mov_b32_e32 v149, 0
	v_mov_b32_e32 v150, 0
	v_mov_b32_e32 v151, 0
	v_dot2c_f32_bf16_e32 v144, v101, v140
	v_dot2c_f32_bf16_e32 v145, v102, v140
	v_dot2c_f32_bf16_e32 v146, v101, v72
	v_dot2c_f32_bf16_e32 v147, v102, v72
	v_dot2c_f32_bf16_e32 v148, v101, v64
	v_dot2c_f32_bf16_e32 v149, v102, v64
	v_dot2c_f32_bf16_e32 v150, v101, v56
	v_dot2c_f32_bf16_e32 v151, v102, v56
	v_dot2c_f32_bf16_e32 v144, v103, v141
	v_dot2c_f32_bf16_e32 v145, v104, v141
	v_dot2c_f32_bf16_e32 v146, v103, v73
	v_dot2c_f32_bf16_e32 v147, v104, v73
	v_dot2c_f32_bf16_e32 v148, v103, v65
	v_dot2c_f32_bf16_e32 v149, v104, v65
	v_dot2c_f32_bf16_e32 v150, v103, v57
	v_dot2c_f32_bf16_e32 v151, v104, v57
	v_dot2c_f32_bf16_e32 v144, v105, v142
	v_dot2c_f32_bf16_e32 v145, v106, v142
	v_dot2c_f32_bf16_e32 v146, v105, v74
	v_dot2c_f32_bf16_e32 v147, v106, v74
	v_dot2c_f32_bf16_e32 v148, v105, v66
	v_dot2c_f32_bf16_e32 v149, v106, v66
	v_dot2c_f32_bf16_e32 v150, v105, v58
	v_dot2c_f32_bf16_e32 v151, v106, v58
	v_dot2c_f32_bf16_e32 v144, v107, v143
	v_dot2c_f32_bf16_e32 v145, v108, v143
	v_dot2c_f32_bf16_e32 v146, v107, v75
	v_dot2c_f32_bf16_e32 v147, v108, v75
	v_dot2c_f32_bf16_e32 v148, v107, v67
	v_dot2c_f32_bf16_e32 v149, v108, v67
	v_dot2c_f32_bf16_e32 v150, v107, v59
	v_dot2c_f32_bf16_e32 v151, v108, v59
	v_dot2c_f32_bf16_e32 v144, v109, v136
	v_dot2c_f32_bf16_e32 v145, v110, v136
	v_dot2c_f32_bf16_e32 v146, v109, v68
	v_dot2c_f32_bf16_e32 v147, v110, v68
	v_dot2c_f32_bf16_e32 v148, v109, v60
	v_dot2c_f32_bf16_e32 v149, v110, v60
	v_dot2c_f32_bf16_e32 v150, v109, v52
	v_dot2c_f32_bf16_e32 v151, v110, v52
	v_dot2c_f32_bf16_e32 v144, v111, v137
	v_dot2c_f32_bf16_e32 v145, v112, v137
	v_dot2c_f32_bf16_e32 v146, v111, v69
	v_dot2c_f32_bf16_e32 v147, v112, v69
	v_dot2c_f32_bf16_e32 v148, v111, v61
	v_dot2c_f32_bf16_e32 v149, v112, v61
	v_dot2c_f32_bf16_e32 v150, v111, v53
	v_dot2c_f32_bf16_e32 v151, v112, v53
	v_dot2c_f32_bf16_e32 v144, v113, v138
	v_dot2c_f32_bf16_e32 v145, v114, v138
	v_dot2c_f32_bf16_e32 v146, v113, v70
	v_dot2c_f32_bf16_e32 v147, v114, v70
	v_dot2c_f32_bf16_e32 v148, v113, v62
	v_dot2c_f32_bf16_e32 v149, v114, v62
	v_dot2c_f32_bf16_e32 v150, v113, v54
	v_dot2c_f32_bf16_e32 v151, v114, v54
	v_dot2c_f32_bf16_e32 v144, v115, v139
	v_dot2c_f32_bf16_e32 v145, v116, v139
	v_dot2c_f32_bf16_e32 v146, v115, v71
	v_dot2c_f32_bf16_e32 v147, v116, v71
	v_dot2c_f32_bf16_e32 v148, v115, v63
	v_dot2c_f32_bf16_e32 v149, v116, v63
	v_dot2c_f32_bf16_e32 v150, v115, v55
	v_dot2c_f32_bf16_e32 v151, v116, v55
	v_add_u32_e32 v97, s12, v99
	v_add_u32_e32 v0, 32, v97
	v_add_u32_e32 v60, 48, v97
	v_pk_mul_f32 v[152:153], v[2:3], v[90:91]
	v_pk_mul_f32 v[154:155], v[94:95], v[90:91]
	v_sub_f32_e32 v152, v152, v153
	v_add_f32_e32 v153, v154, v155
	v_pk_add_f32 v[90:91], v[144:145], v[152:153]
	ds_write2st64_b32 v97, v90, v91 offset1:1
	v_pk_mul_f32 v[152:153], v[2:3], v[90:91]
	v_pk_mul_f32 v[154:155], v[94:95], v[90:91]
	v_sub_f32_e32 v152, v152, v153
	v_add_f32_e32 v153, v154, v155
	v_pk_add_f32 v[90:91], v[146:147], v[152:153]
	ds_write2_b32 v97, v90, v91 offset0:132 offset1:196
	v_pk_mul_f32 v[152:153], v[2:3], v[90:91]
	v_pk_mul_f32 v[154:155], v[94:95], v[90:91]
	v_sub_f32_e32 v152, v152, v153
	v_add_f32_e32 v153, v154, v155
	v_pk_add_f32 v[90:91], v[148:149], v[152:153]
	ds_write2st64_b32 v0, v90, v91 offset0:4 offset1:5
	v_pk_mul_f32 v[152:153], v[2:3], v[90:91]
	v_pk_mul_f32 v[154:155], v[94:95], v[90:91]
	v_sub_f32_e32 v152, v152, v153
	v_add_f32_e32 v153, v154, v155
	v_pk_add_f32 v[90:91], v[150:151], v[152:153]
	ds_write2st64_b32 v60, v90, v91 offset0:6 offset1:7
	s_addk_i32 s12, 0x840
	s_cmpk_eq_i32 s12, 0x2100
	s_mov_b32 s14, s13
	s_cbranch_scc0 .LBB0_150
; __device__ __forceinline__ float gelu_t(float x) { const float p = __builtin_fmaf(x * x, -0.10294324f, -2.30220819f); return x * __builtin_amdgcn_rcpf(1.f + __builtin_amdgcn_exp2f(x * p)); }
; #define LAS __attribute__((address_space(3)))
; __device__ __forceinline__ unsigned f2bf(float f) { unsigned u = __builtin_bit_cast(unsigned, f); return (u + 0x7fffu + ((u >> 16) & 1u)) >> 16; }
; __device__ __forceinline__ void ssm_pass3h(CArgs* ap, const float* COEF, int l, const bf16_t* PROJ, const float* SST, bf16_t* YS, LAS unsigned char* wlds, int unit, int lane) {
;     ...
;         asm volatile("s_waitcnt lgkmcnt(0)" ::: "memory");
;         f32x4 y = (f32x4){0.f, 0.f, 0.f, 0.f};
; #pragma unroll
;         for (int j = 0; j < 8; ++j) {
;             const f32x4 a4 = *(const LAS f32x4*)(Hf + fr * 132 + 16 * j + 4 * fq);
; #pragma unroll
;             for (int r = 0; r < 4; ++r) y = __builtin_amdgcn_mfma_f32_16x16x4f32(a4[r], cmB[4 * j + r], y, 0, 0, 0);
;         }
;         asm volatile("s_waitcnt lgkmcnt(0)" ::: "memory");
; #pragma unroll
;         for (int i = 0; i < 4; ++i) {
;             const size_t row = row0 + 16 * blk + 4 * fq + i;
;             YS[row * 512 + g * 16 + fr] = (bf16_t)f2bf(gelu_t(y[i] + dsk * __uint_as_float(((unsigned)uq[i]) << 16)));
;         }
	s_waitcnt lgkmcnt(0)
	ds_read_b128 v[144:147], v100
	ds_read_b128 v[148:151], v100 offset:64
	ds_read_b128 v[152:155], v100 offset:128
	ds_read_b128 v[168:171], v100 offset:192
	ds_read_b128 v[172:175], v100 offset:256
	ds_read_b128 v[176:179], v100 offset:320
	ds_read_b128 v[180:183], v100 offset:384
	ds_read_b128 v[184:187], v100 offset:448
	s_waitcnt vmcnt(11)
	v_lshlrev_b32_e32 v57, 16, v135
	v_mov_b32_e32 v97, v1
	v_or_b32_e32 v0, 1, v96
	v_or_b32_e32 v58, 2, v96
	v_mov_b32_e32 v59, v1
	v_or_b32_e32 v56, 3, v96
	s_add_i32 s11, s11, 1
	s_add_i32 s10, s10, 16
	s_cmp_eq_u32 s11, 8
	v_lshl_add_u64 v[60:61], v[96:97], 0, s[0:1]
	v_lshlrev_b64 v[60:61], 10, v[60:61]
	v_lshl_add_u64 v[60:61], v[92:93], 0, v[60:61]
	s_waitcnt lgkmcnt(6)
	v_mfma_f32_16x16x4_f32 v[52:55], v144, v4, 0
	v_mfma_f32_16x16x4_f32 v[188:191], v148, v8, 0
	v_mfma_f32_16x16x4_f32 v[52:55], v145, v5, v[52:55]
	v_mfma_f32_16x16x4_f32 v[188:191], v149, v9, v[188:191]
	v_mfma_f32_16x16x4_f32 v[52:55], v146, v6, v[52:55]
	v_mfma_f32_16x16x4_f32 v[188:191], v150, v10, v[188:191]
	v_mfma_f32_16x16x4_f32 v[52:55], v147, v7, v[52:55]
	v_mfma_f32_16x16x4_f32 v[188:191], v151, v11, v[188:191]
	s_waitcnt lgkmcnt(4)
	v_mfma_f32_16x16x4_f32 v[52:55], v152, v12, v[52:55]
	v_mfma_f32_16x16x4_f32 v[188:191], v168, v16, v[188:191]
	v_mfma_f32_16x16x4_f32 v[52:55], v153, v13, v[52:55]
	v_mfma_f32_16x16x4_f32 v[188:191], v169, v17, v[188:191]
	v_mfma_f32_16x16x4_f32 v[52:55], v154, v14, v[52:55]
	v_mfma_f32_16x16x4_f32 v[188:191], v170, v18, v[188:191]
	v_mfma_f32_16x16x4_f32 v[52:55], v155, v15, v[52:55]
	v_mfma_f32_16x16x4_f32 v[188:191], v171, v19, v[188:191]
	s_waitcnt lgkmcnt(2)
	v_mfma_f32_16x16x4_f32 v[52:55], v172, v89, v[52:55]
	v_mfma_f32_16x16x4_f32 v[188:191], v176, v120, v[188:191]
	v_mfma_f32_16x16x4_f32 v[52:55], v173, v117, v[52:55]
	v_mfma_f32_16x16x4_f32 v[188:191], v177, v121, v[188:191]
	v_mfma_f32_16x16x4_f32 v[52:55], v174, v118, v[52:55]
	v_mfma_f32_16x16x4_f32 v[188:191], v178, v122, v[188:191]
	v_mfma_f32_16x16x4_f32 v[52:55], v175, v119, v[52:55]
	v_mfma_f32_16x16x4_f32 v[188:191], v179, v123, v[188:191]
	s_waitcnt lgkmcnt(0)
	v_mfma_f32_16x16x4_f32 v[52:55], v180, v124, v[52:55]
	v_mfma_f32_16x16x4_f32 v[188:191], v184, v128, v[188:191]
	v_mfma_f32_16x16x4_f32 v[52:55], v181, v125, v[52:55]
	v_mfma_f32_16x16x4_f32 v[188:191], v185, v129, v[188:191]
	v_mfma_f32_16x16x4_f32 v[52:55], v182, v126, v[52:55]
	v_mfma_f32_16x16x4_f32 v[188:191], v186, v130, v[188:191]
	v_mfma_f32_16x16x4_f32 v[52:55], v183, v127, v[52:55]
	v_mfma_f32_16x16x4_f32 v[188:191], v187, v131, v[188:191]
	s_nop 9
	s_nop 1
	v_add_f32_e32 v52, v52, v188
	v_add_f32_e32 v53, v53, v189
	v_add_f32_e32 v54, v54, v190
	v_add_f32_e32 v55, v55, v191
	v_fma_f32 v52, v87, v57, v52
	v_mul_f32_e32 v57, v52, v52
	v_fmamk_f32 v57, v57, 0xbdd2d3e8, v196
	v_mul_f32_e32 v57, v52, v57
	v_exp_f32_e32 v57, v57
	s_nop 0
	v_add_f32_e32 v57, 1.0, v57
	v_rcp_f32_e32 v57, v57
	s_nop 0
	v_mul_f32_e32 v52, v52, v57
	v_bfe_u32 v57, v52, 16, 1
	v_add3_u32 v52, v52, v57, s80
	global_store_short_d16_hi v[60:61], v52, off
	v_lshl_add_u64 v[60:61], v[0:1], 0, s[0:1]
	s_waitcnt vmcnt(11)
	v_lshlrev_b32_e32 v0, 16, v134
	v_fma_f32 v0, v87, v0, v53
	v_mul_f32_e32 v52, v0, v0
	v_fmamk_f32 v52, v52, 0xbdd2d3e8, v196
	v_mul_f32_e32 v52, v0, v52
	v_exp_f32_e32 v52, v52
	v_mov_b32_e32 v57, v1
	v_add_f32_e32 v52, 1.0, v52
	v_rcp_f32_e32 v52, v52
	s_nop 0
	v_mul_f32_e32 v0, v0, v52
	v_bfe_u32 v52, v0, 16, 1
	v_add3_u32 v0, v0, v52, s80
	v_lshlrev_b64 v[52:53], 10, v[60:61]
	v_lshl_add_u64 v[52:53], v[92:93], 0, v[52:53]
	global_store_short_d16_hi v[52:53], v0, off
	s_waitcnt vmcnt(11)
	v_lshlrev_b32_e32 v0, 16, v133
	v_fma_f32 v0, v87, v0, v54
	v_mul_f32_e32 v54, v0, v0
	v_fmamk_f32 v54, v54, 0xbdd2d3e8, v196
	v_mul_f32_e32 v54, v0, v54
	v_exp_f32_e32 v54, v54
	v_lshl_add_u64 v[52:53], v[58:59], 0, s[0:1]
	v_lshlrev_b64 v[52:53], 10, v[52:53]
	v_lshl_add_u64 v[52:53], v[92:93], 0, v[52:53]
	v_add_f32_e32 v54, 1.0, v54
	v_rcp_f32_e32 v54, v54
	s_nop 0
	v_mul_f32_e32 v0, v0, v54
	v_bfe_u32 v54, v0, 16, 1
	v_add3_u32 v0, v0, v54, s80
	global_store_short_d16_hi v[52:53], v0, off
	s_waitcnt vmcnt(11)
	v_lshlrev_b32_e32 v0, 16, v132
	v_fmac_f32_e32 v55, v87, v0
	v_mul_f32_e32 v0, v55, v55
	v_fmamk_f32 v0, v0, 0xbdd2d3e8, v196
	v_mul_f32_e32 v0, v55, v0
	v_exp_f32_e32 v0, v0
	v_lshl_add_u64 v[52:53], v[56:57], 0, s[0:1]
	v_lshlrev_b64 v[52:53], 10, v[52:53]
	v_lshl_add_u64 v[52:53], v[92:93], 0, v[52:53]
	v_add_f32_e32 v0, 1.0, v0
	v_rcp_f32_e32 v0, v0
	s_nop 0
	v_mul_f32_e32 v0, v55, v0
	v_bfe_u32 v54, v0, 16, 1
	v_add3_u32 v0, v0, v54, s80
	global_store_short_d16_hi v[52:53], v0, off
	s_cbranch_scc0 .LBB0_149
	s_add_i32 s9, s9, s33
	s_cmpk_gt_i32 s9, 0xfff
	s_cbranch_scc0 .LBB0_141
